# P5 out-proj epilogue hand-rewritten: x base loads pipelined 5 chunks deep with counted vmcnt instead of load-wait0-store serial chain
# baseline (speedup 1.0000x reference)
.LBB0_757:
	s_lshl_b32 s16, s14, 8
	v_add_u32_e32 v194, s16, v149
	v_lshl_or_b32 v166, s6, 8, v179
	v_readlane_b32 s60, v249, 9
	v_readlane_b32 s61, v249, 10
	s_ashr_i32 s0, s14, 3
	s_mul_hi_i32 s1, s0, 0x6000
	s_mulk_i32 s0, 0x6000
	s_add_u32 s0, s47, s0
	s_addc_u32 s1, s48, s1
	v_mov_b32_e32 v167, 0
	v_lshl_add_u32 v164, v194, 10, v166
	v_mov_b32_e32 v165, 0
	v_lshl_add_u64 v[170:171], v[166:167], 2, s[0:1]
	v_lshl_add_u64 v[172:173], v[164:165], 2, s[60:61]
	v_lshlrev_b32_e32 v144, 1, v164
	global_load_dwordx4 v[128:131], v[170:171], off
	global_load_dwordx4 v[132:135], v[170:171], off offset:16
	s_mov_b32 s62, 0x10000
	s_mov_b32 s63, 0
	s_mov_b32 s64, 0x50000
	s_mov_b32 s65, 0
	s_mov_b32 s66, 0x8000
	s_mov_b32 s67, 0x10000
	s_mov_b32 s68, 0x18000
	s_mov_b32 s69, 0x40000
	s_mov_b32 s70, 0x48000
	s_mov_b32 s71, 0x50000
	s_mov_b32 s72, 0x58000
	v_mov_b64_e32 v[174:175], v[172:173]
	global_load_dwordx4 v[200:203], v[174:175], off
	global_load_dwordx4 v[204:207], v[174:175], off offset:16
	v_lshl_add_u64 v[174:175], v[174:175], 0, s[62:63]
	global_load_dwordx4 v[208:211], v[174:175], off
	global_load_dwordx4 v[212:215], v[174:175], off offset:16
	global_load_dwordx4 v[186:189], v[170:171], off offset:512
	global_load_dwordx4 v[190:193], v[170:171], off offset:528
	v_lshl_add_u64 v[174:175], v[174:175], 0, s[62:63]
	global_load_dwordx4 v[216:219], v[174:175], off
	global_load_dwordx4 v[220:223], v[174:175], off offset:16
	v_lshl_add_u64 v[174:175], v[174:175], 0, s[62:63]
	global_load_dwordx4 v[224:227], v[174:175], off
	global_load_dwordx4 v[228:231], v[174:175], off offset:16
	v_lshl_add_u64 v[174:175], v[174:175], 0, s[64:65]
	global_load_dwordx4 v[232:235], v[174:175], off
	global_load_dwordx4 v[236:239], v[174:175], off offset:16
	v_lshl_add_u64 v[174:175], v[174:175], 0, s[62:63]
	global_load_dwordx4 v[240:243], v[174:175], off
	global_load_dwordx4 v[244:247], v[174:175], off offset:16
	s_waitcnt vmcnt(12)
	v_pk_fma_f32 v[124:125], v[124:125], v[128:129], v[200:201]
	v_pk_fma_f32 v[126:127], v[126:127], v[130:131], v[202:203]
	v_pk_fma_f32 v[120:121], v[120:121], v[132:133], v[204:205]
	v_pk_fma_f32 v[122:123], v[122:123], v[134:135], v[206:207]
	v_cvt_pk_bf16_f32 v204, v124, v125
	v_cvt_pk_bf16_f32 v205, v126, v127
	v_cvt_pk_bf16_f32 v206, v120, v121
	v_cvt_pk_bf16_f32 v207, v122, v123
	buffer_store_dwordx4 v[204:207], v144, s[8:11], 0 offen sc1
	v_lshl_add_u64 v[174:175], v[174:175], 0, s[62:63]
	global_load_dwordx4 v[200:203], v[174:175], off
	global_load_dwordx4 v[204:207], v[174:175], off offset:16
	s_waitcnt vmcnt(13)
	v_pk_fma_f32 v[116:117], v[116:117], v[128:129], v[208:209]
	v_pk_fma_f32 v[118:119], v[118:119], v[130:131], v[210:211]
	v_pk_fma_f32 v[112:113], v[112:113], v[132:133], v[212:213]
	v_pk_fma_f32 v[114:115], v[114:115], v[134:135], v[214:215]
	v_cvt_pk_bf16_f32 v212, v116, v117
	v_cvt_pk_bf16_f32 v213, v118, v119
	v_cvt_pk_bf16_f32 v214, v112, v113
	v_cvt_pk_bf16_f32 v215, v114, v115
	buffer_store_dwordx4 v[212:215], v144, s[8:11], s66 offen sc1
	v_lshl_add_u64 v[174:175], v[174:175], 0, s[62:63]
	global_load_dwordx4 v[208:211], v[174:175], off
	global_load_dwordx4 v[212:215], v[174:175], off offset:16
	s_waitcnt vmcnt(12)
	v_pk_fma_f32 v[108:109], v[108:109], v[128:129], v[216:217]
	v_pk_fma_f32 v[110:111], v[110:111], v[130:131], v[218:219]
	v_pk_fma_f32 v[104:105], v[104:105], v[132:133], v[220:221]
	v_pk_fma_f32 v[106:107], v[106:107], v[134:135], v[222:223]
	v_cvt_pk_bf16_f32 v220, v108, v109
	v_cvt_pk_bf16_f32 v221, v110, v111
	v_cvt_pk_bf16_f32 v222, v104, v105
	v_cvt_pk_bf16_f32 v223, v106, v107
	buffer_store_dwordx4 v[220:223], v144, s[8:11], s67 offen sc1
	v_mov_b64_e32 v[174:175], v[172:173]
	global_load_dwordx4 v[216:219], v[174:175], off offset:512
	global_load_dwordx4 v[220:223], v[174:175], off offset:528
	s_waitcnt vmcnt(13)
	v_pk_fma_f32 v[100:101], v[100:101], v[128:129], v[224:225]
	v_pk_fma_f32 v[102:103], v[102:103], v[130:131], v[226:227]
	v_pk_fma_f32 v[96:97], v[96:97], v[132:133], v[228:229]
	v_pk_fma_f32 v[98:99], v[98:99], v[134:135], v[230:231]
	v_cvt_pk_bf16_f32 v228, v100, v101
	v_cvt_pk_bf16_f32 v229, v102, v103
	v_cvt_pk_bf16_f32 v230, v96, v97
	v_cvt_pk_bf16_f32 v231, v98, v99
	buffer_store_dwordx4 v[228:231], v144, s[8:11], s68 offen sc1
	v_lshl_add_u64 v[174:175], v[174:175], 0, s[62:63]
	global_load_dwordx4 v[224:227], v[174:175], off offset:512
	global_load_dwordx4 v[228:231], v[174:175], off offset:528
	s_waitcnt vmcnt(14)
	v_pk_fma_f32 v[92:93], v[92:93], v[128:129], v[232:233]
	v_pk_fma_f32 v[94:95], v[94:95], v[130:131], v[234:235]
	v_pk_fma_f32 v[88:89], v[88:89], v[132:133], v[236:237]
	v_pk_fma_f32 v[90:91], v[90:91], v[134:135], v[238:239]
	v_cvt_pk_bf16_f32 v236, v92, v93
	v_cvt_pk_bf16_f32 v237, v94, v95
	v_cvt_pk_bf16_f32 v238, v88, v89
	v_cvt_pk_bf16_f32 v239, v90, v91
	buffer_store_dwordx4 v[236:239], v144, s[8:11], s69 offen sc1
	v_lshl_add_u64 v[174:175], v[174:175], 0, s[62:63]
	global_load_dwordx4 v[232:235], v[174:175], off offset:512
	global_load_dwordx4 v[236:239], v[174:175], off offset:528
	s_waitcnt vmcnt(15)
	v_pk_fma_f32 v[84:85], v[84:85], v[128:129], v[240:241]
	v_pk_fma_f32 v[86:87], v[86:87], v[130:131], v[242:243]
	v_pk_fma_f32 v[80:81], v[80:81], v[132:133], v[244:245]
	v_pk_fma_f32 v[82:83], v[82:83], v[134:135], v[246:247]
	v_cvt_pk_bf16_f32 v244, v84, v85
	v_cvt_pk_bf16_f32 v245, v86, v87
	v_cvt_pk_bf16_f32 v246, v80, v81
	v_cvt_pk_bf16_f32 v247, v82, v83
	buffer_store_dwordx4 v[244:247], v144, s[8:11], s70 offen sc1
	v_lshl_add_u64 v[174:175], v[174:175], 0, s[62:63]
	global_load_dwordx4 v[240:243], v[174:175], off offset:512
	global_load_dwordx4 v[244:247], v[174:175], off offset:528
	s_waitcnt vmcnt(15)
	v_pk_fma_f32 v[76:77], v[76:77], v[128:129], v[200:201]
	v_pk_fma_f32 v[78:79], v[78:79], v[130:131], v[202:203]
	v_pk_fma_f32 v[72:73], v[72:73], v[132:133], v[204:205]
	v_pk_fma_f32 v[74:75], v[74:75], v[134:135], v[206:207]
	v_cvt_pk_bf16_f32 v204, v76, v77
	v_cvt_pk_bf16_f32 v205, v78, v79
	v_cvt_pk_bf16_f32 v206, v72, v73
	v_cvt_pk_bf16_f32 v207, v74, v75
	buffer_store_dwordx4 v[204:207], v144, s[8:11], s71 offen sc1
	v_lshl_add_u64 v[174:175], v[174:175], 0, s[64:65]
	global_load_dwordx4 v[200:203], v[174:175], off offset:512
	global_load_dwordx4 v[204:207], v[174:175], off offset:528
	s_waitcnt vmcnt(15)
	v_pk_fma_f32 v[64:65], v[64:65], v[128:129], v[208:209]
	v_pk_fma_f32 v[66:67], v[66:67], v[130:131], v[210:211]
	v_pk_fma_f32 v[56:57], v[56:57], v[132:133], v[212:213]
	v_pk_fma_f32 v[58:59], v[58:59], v[134:135], v[214:215]
	v_cvt_pk_bf16_f32 v212, v64, v65
	v_cvt_pk_bf16_f32 v213, v66, v67
	v_cvt_pk_bf16_f32 v214, v56, v57
	v_cvt_pk_bf16_f32 v215, v58, v59
	buffer_store_dwordx4 v[212:215], v144, s[8:11], s72 offen sc1
	v_lshl_add_u64 v[174:175], v[174:175], 0, s[62:63]
	global_load_dwordx4 v[208:211], v[174:175], off offset:512
	global_load_dwordx4 v[212:215], v[174:175], off offset:528
	s_waitcnt vmcnt(15)
	v_pk_fma_f32 v[68:69], v[68:69], v[186:187], v[216:217]
	v_pk_fma_f32 v[70:71], v[70:71], v[188:189], v[218:219]
	v_pk_fma_f32 v[60:61], v[60:61], v[190:191], v[220:221]
	v_pk_fma_f32 v[62:63], v[62:63], v[192:193], v[222:223]
	v_cvt_pk_bf16_f32 v220, v68, v69
	v_cvt_pk_bf16_f32 v221, v70, v71
	v_cvt_pk_bf16_f32 v222, v60, v61
	v_cvt_pk_bf16_f32 v223, v62, v63
	buffer_store_dwordx4 v[220:223], v144, s[8:11], 0 offen offset:256 sc1
	v_lshl_add_u64 v[174:175], v[174:175], 0, s[62:63]
	global_load_dwordx4 v[216:219], v[174:175], off offset:512
	global_load_dwordx4 v[220:223], v[174:175], off offset:528
	s_waitcnt vmcnt(15)
	v_pk_fma_f32 v[52:53], v[52:53], v[186:187], v[224:225]
	v_pk_fma_f32 v[54:55], v[54:55], v[188:189], v[226:227]
	v_pk_fma_f32 v[48:49], v[48:49], v[190:191], v[228:229]
	v_pk_fma_f32 v[50:51], v[50:51], v[192:193], v[230:231]
	v_cvt_pk_bf16_f32 v228, v52, v53
	v_cvt_pk_bf16_f32 v229, v54, v55
	v_cvt_pk_bf16_f32 v230, v48, v49
	v_cvt_pk_bf16_f32 v231, v50, v51
	buffer_store_dwordx4 v[228:231], v144, s[8:11], s66 offen offset:256 sc1
	v_lshl_add_u64 v[174:175], v[174:175], 0, s[62:63]
	global_load_dwordx4 v[224:227], v[174:175], off offset:512
	global_load_dwordx4 v[228:231], v[174:175], off offset:528
	s_waitcnt vmcnt(15)
	v_pk_fma_f32 v[44:45], v[44:45], v[186:187], v[232:233]
	v_pk_fma_f32 v[46:47], v[46:47], v[188:189], v[234:235]
	v_pk_fma_f32 v[40:41], v[40:41], v[190:191], v[236:237]
	v_pk_fma_f32 v[42:43], v[42:43], v[192:193], v[238:239]
	v_cvt_pk_bf16_f32 v236, v44, v45
	v_cvt_pk_bf16_f32 v237, v46, v47
	v_cvt_pk_bf16_f32 v238, v40, v41
	v_cvt_pk_bf16_f32 v239, v42, v43
	buffer_store_dwordx4 v[236:239], v144, s[8:11], s67 offen offset:256 sc1
	s_waitcnt vmcnt(13)
	v_pk_fma_f32 v[36:37], v[36:37], v[186:187], v[240:241]
	v_pk_fma_f32 v[38:39], v[38:39], v[188:189], v[242:243]
	v_pk_fma_f32 v[32:33], v[32:33], v[190:191], v[244:245]
	v_pk_fma_f32 v[34:35], v[34:35], v[192:193], v[246:247]
	v_cvt_pk_bf16_f32 v244, v36, v37
	v_cvt_pk_bf16_f32 v245, v38, v39
	v_cvt_pk_bf16_f32 v246, v32, v33
	v_cvt_pk_bf16_f32 v247, v34, v35
	buffer_store_dwordx4 v[244:247], v144, s[8:11], s68 offen offset:256 sc1
	s_waitcnt vmcnt(11)
	v_pk_fma_f32 v[28:29], v[28:29], v[186:187], v[200:201]
	v_pk_fma_f32 v[30:31], v[30:31], v[188:189], v[202:203]
	v_pk_fma_f32 v[24:25], v[24:25], v[190:191], v[204:205]
	v_pk_fma_f32 v[26:27], v[26:27], v[192:193], v[206:207]
	v_cvt_pk_bf16_f32 v204, v28, v29
	v_cvt_pk_bf16_f32 v205, v30, v31
	v_cvt_pk_bf16_f32 v206, v24, v25
	v_cvt_pk_bf16_f32 v207, v26, v27
	buffer_store_dwordx4 v[204:207], v144, s[8:11], s69 offen offset:256 sc1
	s_waitcnt vmcnt(9)
	v_pk_fma_f32 v[20:21], v[20:21], v[186:187], v[208:209]
	v_pk_fma_f32 v[22:23], v[22:23], v[188:189], v[210:211]
	v_pk_fma_f32 v[16:17], v[16:17], v[190:191], v[212:213]
	v_pk_fma_f32 v[18:19], v[18:19], v[192:193], v[214:215]
	v_cvt_pk_bf16_f32 v212, v20, v21
	v_cvt_pk_bf16_f32 v213, v22, v23
	v_cvt_pk_bf16_f32 v214, v16, v17
	v_cvt_pk_bf16_f32 v215, v18, v19
	buffer_store_dwordx4 v[212:215], v144, s[8:11], s70 offen offset:256 sc1
	s_waitcnt vmcnt(7)
	v_pk_fma_f32 v[12:13], v[12:13], v[186:187], v[216:217]
	v_pk_fma_f32 v[14:15], v[14:15], v[188:189], v[218:219]
	v_pk_fma_f32 v[8:9], v[8:9], v[190:191], v[220:221]
	v_pk_fma_f32 v[10:11], v[10:11], v[192:193], v[222:223]
	v_cvt_pk_bf16_f32 v220, v12, v13
	v_cvt_pk_bf16_f32 v221, v14, v15
	v_cvt_pk_bf16_f32 v222, v8, v9
	v_cvt_pk_bf16_f32 v223, v10, v11
	buffer_store_dwordx4 v[220:223], v144, s[8:11], s71 offen offset:256 sc1
	s_waitcnt vmcnt(5)
	v_pk_fma_f32 v[4:5], v[4:5], v[186:187], v[224:225]
	v_pk_fma_f32 v[6:7], v[6:7], v[188:189], v[226:227]
	v_pk_fma_f32 v[0:1], v[0:1], v[190:191], v[228:229]
	v_pk_fma_f32 v[2:3], v[2:3], v[192:193], v[230:231]
	v_cvt_pk_bf16_f32 v228, v4, v5
	v_cvt_pk_bf16_f32 v229, v6, v7
	v_cvt_pk_bf16_f32 v230, v0, v1
	v_cvt_pk_bf16_f32 v231, v2, v3
	buffer_store_dwordx4 v[228:231], v144, s[8:11], s72 offen offset:256 sc1
	s_mov_b64 s[0:1], -1
	s_and_b64 vcc, exec, s[26:27]
	s_cbranch_vccz .LBB0_768
	s_waitcnt vmcnt(0)
	s_barrier
	s_and_saveexec_b64 s[0:1], s[92:93]
	s_cbranch_execz .LBB0_764
	s_mov_b64 s[42:43], exec
	v_mbcnt_lo_u32_b32 v0, s42, 0
	v_mbcnt_hi_u32_b32 v0, s43, v0
	v_cmp_eq_u32_e32 vcc, 0, v0
	s_and_saveexec_b64 s[4:5], vcc
	s_cbranch_execz .LBB0_761
	s_ashr_i32 s15, s14, 31
	s_lshl_b64 s[60:61], s[14:15], 2
	v_readlane_b32 s62, v249, 31
	v_readlane_b32 s63, v249, 32
	s_add_u32 s60, s62, s60
	s_addc_u32 s61, s63, s61
	s_bcnt1_i32_b64 s15, s[42:43]
	v_mov_b32_e32 v1, s15
	global_atomic_add v1, v145, v1, s[60:61] sc0
